# APD: prompt attention unit prologue - the 12 ds_bpermute exchanges of the two interleaved lane reductions replaced by DPP / permlane16-32 swaps
# baseline (speedup 1.0000x reference)
; __device__ __forceinline__ void attn_unit(const Args& a, LAS unsigned char* lds, const int mode, const int h, const int qb, const int tid_in, const int lane_in, const int wave) {
;     ...
;     if (mode == 0 && qb > 0) {
;         float dsc = 0.f;
; #pragma unroll
;         for (int d0 = 0; d0 < 4; ++d0) { const u32x4 kw = *(const u32x4*)(Kb + (size_t)qrow * D + h * HD + d0 * 16 + hi * 8); const u32x4 qw = __builtin_bit_cast(u32x4, qr[d0]);
;             const unsigned kk[4] = {kw.x, kw.y, kw.z, kw.w}; const unsigned qq[4] = {qw.x, qw.y, qw.z, qw.w};
; #pragma unroll
;             for (int e = 0; e < 4; ++e) dsc += __uint_as_float(kk[e] << 16) * __uint_as_float(qq[e] << 16) + __uint_as_float(kk[e] & 0xffff0000u) * __uint_as_float(qq[e] & 0xffff0000u); }
;         dsc += __shfl_xor(dsc, 32);
; #pragma unroll
;         for (int o = 1; o < 32; o <<= 1) dsc = fminf(dsc, __shfl_xor(dsc, o));
;         float qsq = 0.f;
; #pragma unroll
;         for (int d0 = 0; d0 < 4; ++d0) { const u32x4 qw = __builtin_bit_cast(u32x4, qr[d0]); const unsigned qq[4] = {qw.x, qw.y, qw.z, qw.w};
; #pragma unroll
;             for (int e = 0; e < 4; ++e) { const float lo = __uint_as_float(qq[e] << 16), hi_ = __uint_as_float(qq[e] & 0xffff0000u); qsq += lo * lo + hi_ * hi_; } }
;         qsq += __shfl_xor(qsq, 32);
.LBB0_501:
	s_andn2_b64 vcc, exec, s[0:1]
	s_cbranch_vccnz .LBB0_542
	s_add_i32 s0, s68, 0xffffff00
	s_and_b32 s17, s68, 15
	s_lshr_b32 s0, s0, 4
	s_sub_i32 s1, 63, s0
	s_mul_i32 s2, s17, 0x11000
	v_readlane_b32 s3, v254, 28
	s_add_u32 s8, s3, s2
	v_readlane_b32 s2, v254, 30
	v_mov_b32_e32 v1, v134
	s_addc_u32 s9, s2, 0
	s_lshl_b32 s2, s1, 8
	v_readlane_b32 s3, v254, 25
	s_add_i32 s3, s2, s3
	v_and_b32_e32 v6, 31, v1
	v_or_b32_e32 v92, s3, v6
	s_lshl_b32 s15, s17, 8
	s_lshr_b32 s3, s3, 6
	v_mov_b32_e32 v93, v0
	v_readlane_b32 s4, v254, 26
	s_add_i32 s3, s3, s15
	v_lshlrev_b64 v[2:3], 11, v[92:93]
	v_readlane_b32 s5, v254, 27
	v_bfe_u32 v7, v1, 5, 1
	s_lshl_b32 s3, s3, 2
	v_lshl_add_u64 v[8:9], s[4:5], 0, v[2:3]
	s_lshl_b32 s72, s17, 7
	v_mov_b32_e32 v14, s3
	v_lshl_add_u64 v[8:9], v[8:9], 0, s[72:73]
	v_lshlrev_b32_e32 v10, 4, v7
	v_mov_b32_e32 v11, v0
	v_lshl_add_u64 v[4:5], v[92:93], 2, s[8:9]
	v_lshl_add_u64 v[12:13], v[8:9], 0, v[10:11]
	global_load_dword v9, v14, s[60:61]
	global_load_dword v10, v[4:5], off
	global_load_dwordx4 v[66:69], v[12:13], off
	global_load_dwordx4 v[70:73], v[12:13], off offset:32
	global_load_dwordx4 v[74:77], v[12:13], off offset:64
	global_load_dwordx4 v[78:81], v[12:13], off offset:96
	s_lshl_b32 s16, s1, 2
	s_lshl_b32 s14, s17, 6
	v_and_b32_e32 v8, 63, v1
	v_lshlrev_b32_e32 v90, 3, v7
	s_cmp_eq_u32 s0, 63
	s_mov_b32 s12, 0
	s_cbranch_scc1 .LBB0_514
	v_lshl_add_u64 v[2:3], s[38:39], 0, v[2:3]
	s_lshl_b32 s72, s14, 1
	v_lshl_add_u64 v[2:3], v[2:3], 0, s[72:73]
	v_lshlrev_b32_e32 v4, 1, v90
	v_mov_b32_e32 v5, v0
	v_lshl_add_u64 v[2:3], v[2:3], 0, v[4:5]
	global_load_dwordx4 v[16:19], v[2:3], off
	global_load_dwordx4 v[24:27], v[2:3], off offset:32
	global_load_dwordx4 v[32:35], v[2:3], off offset:64
	v_cmp_gt_u32_e64 s[98:99], 32, v138
	v_and_b32_e32 v253, 16, v138
	v_cmp_eq_u32_e64 s[100:101], 0, v253
	s_waitcnt vmcnt(6)
	v_and_b32_e32 v12, 0xffff0000, v66
	v_lshlrev_b32_e32 v11, 16, v66
	v_and_b32_e32 v15, 0xffff0000, v67
	v_lshlrev_b32_e32 v13, 16, v67
	s_waitcnt vmcnt(5)
	v_and_b32_e32 v21, 0xffff0000, v70
	v_and_b32_e32 v23, 0xffff0000, v71
	s_waitcnt vmcnt(4)
	v_and_b32_e32 v29, 0xffff0000, v74
	v_and_b32_e32 v31, 0xffff0000, v75
	s_waitcnt vmcnt(3)
	v_and_b32_e32 v38, 0xffff0000, v78
	v_lshlrev_b32_e32 v37, 16, v78
	v_and_b32_e32 v39, 0xffff0000, v79
	v_and_b32_e32 v40, 0xffff0000, v80
	v_and_b32_e32 v41, 0xffff0000, v81
	s_waitcnt vmcnt(2)
	v_and_b32_e32 v5, 0xffff0000, v16
	v_lshlrev_b32_e32 v4, 16, v16
	v_mul_f32_e32 v5, v12, v5
	v_fmac_f32_e32 v5, v11, v4
	v_and_b32_e32 v14, 0xffff0000, v17
	v_add_f32_e32 v4, 0, v5
	v_lshlrev_b32_e32 v5, 16, v17
	v_mul_f32_e32 v14, v15, v14
	v_fmac_f32_e32 v14, v13, v5
	v_and_b32_e32 v16, 0xffff0000, v18
	v_and_b32_e32 v17, 0xffff0000, v68
	v_add_f32_e32 v4, v14, v4
	v_lshlrev_b32_e32 v5, 16, v18
	v_lshlrev_b32_e32 v14, 16, v68
	v_mul_f32_e32 v16, v17, v16
	v_fmac_f32_e32 v16, v14, v5
	v_lshlrev_b32_e32 v5, 16, v19
	v_and_b32_e32 v19, 0xffff0000, v19
	v_and_b32_e32 v18, 0xffff0000, v69
	v_add_f32_e32 v4, v16, v4
	v_lshlrev_b32_e32 v16, 16, v69
	v_mul_f32_e32 v19, v18, v19
	v_fmac_f32_e32 v19, v16, v5
	s_waitcnt vmcnt(1)
	v_and_b32_e32 v20, 0xffff0000, v24
	v_add_f32_e32 v4, v19, v4
	v_lshlrev_b32_e32 v5, 16, v24
	v_lshlrev_b32_e32 v19, 16, v70
	v_mul_f32_e32 v20, v21, v20
	v_fmac_f32_e32 v20, v19, v5
	v_and_b32_e32 v22, 0xffff0000, v25
	v_add_f32_e32 v4, v20, v4
	v_lshlrev_b32_e32 v5, 16, v25
	v_lshlrev_b32_e32 v20, 16, v71
	v_mul_f32_e32 v22, v23, v22
	v_fmac_f32_e32 v22, v20, v5
	v_and_b32_e32 v24, 0xffff0000, v26
	v_and_b32_e32 v25, 0xffff0000, v72
	v_add_f32_e32 v4, v22, v4
	v_lshlrev_b32_e32 v5, 16, v26
	v_lshlrev_b32_e32 v22, 16, v72
	v_mul_f32_e32 v24, v25, v24
	v_fmac_f32_e32 v24, v22, v5
	v_lshlrev_b32_e32 v5, 16, v27
	v_and_b32_e32 v27, 0xffff0000, v27
	v_and_b32_e32 v26, 0xffff0000, v73
	v_add_f32_e32 v4, v24, v4
	v_lshlrev_b32_e32 v24, 16, v73
	v_mul_f32_e32 v27, v26, v27
	v_fmac_f32_e32 v27, v24, v5
	s_waitcnt vmcnt(0)
	v_and_b32_e32 v28, 0xffff0000, v32
	v_add_f32_e32 v4, v27, v4
	v_lshlrev_b32_e32 v5, 16, v32
	v_lshlrev_b32_e32 v27, 16, v74
	v_mul_f32_e32 v28, v29, v28
	v_fmac_f32_e32 v28, v27, v5
	v_and_b32_e32 v30, 0xffff0000, v33
	v_add_f32_e32 v4, v28, v4
	v_lshlrev_b32_e32 v5, 16, v33
	v_lshlrev_b32_e32 v28, 16, v75
	v_mul_f32_e32 v30, v31, v30
	v_fmac_f32_e32 v30, v28, v5
	v_and_b32_e32 v32, 0xffff0000, v34
	v_and_b32_e32 v33, 0xffff0000, v76
	v_add_f32_e32 v4, v30, v4
	v_lshlrev_b32_e32 v5, 16, v34
	v_lshlrev_b32_e32 v30, 16, v76
	v_mul_f32_e32 v32, v33, v32
	v_fmac_f32_e32 v32, v30, v5
	v_lshlrev_b32_e32 v5, 16, v35
	v_and_b32_e32 v35, 0xffff0000, v35
	v_and_b32_e32 v34, 0xffff0000, v77
	v_add_f32_e32 v4, v32, v4
	v_lshlrev_b32_e32 v32, 16, v77
	v_mul_f32_e32 v35, v34, v35
	v_fmac_f32_e32 v35, v32, v5
	v_add_f32_e32 v35, v35, v4
	global_load_dwordx4 v[2:5], v[2:3], off offset:96
	v_mul_f32_e32 v12, v12, v12
	v_fmac_f32_e32 v12, v11, v11
	v_mul_f32_e32 v11, v15, v15
	v_fmac_f32_e32 v11, v13, v13
	v_add_f32_e32 v11, v12, v11
	v_mul_f32_e32 v12, v17, v17
	v_fmac_f32_e32 v12, v14, v14
	v_add_f32_e32 v11, v12, v11
	v_mul_f32_e32 v12, v18, v18
	v_fmac_f32_e32 v12, v16, v16
	v_add_f32_e32 v11, v12, v11
	v_mul_f32_e32 v12, v21, v21
	v_fmac_f32_e32 v12, v19, v19
	v_add_f32_e32 v11, v12, v11
	v_mul_f32_e32 v12, v23, v23
	v_fmac_f32_e32 v12, v20, v20
	v_add_f32_e32 v11, v12, v11
	v_mul_f32_e32 v12, v25, v25
	v_fmac_f32_e32 v12, v22, v22
	v_add_f32_e32 v11, v12, v11
	v_mul_f32_e32 v12, v26, v26
	v_fmac_f32_e32 v12, v24, v24
	v_add_f32_e32 v11, v12, v11
	v_mul_f32_e32 v12, v29, v29
	v_fmac_f32_e32 v12, v27, v27
	v_add_f32_e32 v11, v12, v11
	v_mul_f32_e32 v12, v31, v31
	v_fmac_f32_e32 v12, v28, v28
	v_add_f32_e32 v11, v12, v11
	v_mul_f32_e32 v12, v33, v33
	v_fmac_f32_e32 v12, v30, v30
	v_add_f32_e32 v11, v12, v11
	v_mul_f32_e32 v12, v34, v34
	v_fmac_f32_e32 v12, v32, v32
	v_add_f32_e32 v11, v12, v11
	v_mul_f32_e32 v12, v38, v38
	v_fmac_f32_e32 v12, v37, v37
	v_add_f32_e32 v11, v12, v11
	v_mul_f32_e32 v12, v39, v39
	s_waitcnt vmcnt(0)
; #define LAS __attribute__((address_space(3)))
; __device__ __forceinline__ void attn_unit(const Args& a, LAS unsigned char* lds, const int mode, const int h, const int qb, const int tid_in, const int lane_in, const int wave) {
;     ...
;         for (int d0 = 0; d0 < 4; ++d0) { const u32x4 kw = *(const u32x4*)(Kb + (size_t)qrow * D + h * HD + d0 * 16 + hi * 8); const u32x4 qw = __builtin_bit_cast(u32x4, qr[d0]);
;             const unsigned kk[4] = {kw.x, kw.y, kw.z, kw.w}; const unsigned qq[4] = {qw.x, qw.y, qw.z, qw.w};
; #pragma unroll
;             for (int e = 0; e < 4; ++e) dsc += __uint_as_float(kk[e] << 16) * __uint_as_float(qq[e] << 16) + __uint_as_float(kk[e] & 0xffff0000u) * __uint_as_float(qq[e] & 0xffff0000u); }
;         dsc += __shfl_xor(dsc, 32);
; #pragma unroll
;         for (int o = 1; o < 32; o <<= 1) dsc = fminf(dsc, __shfl_xor(dsc, o));
;         float qsq = 0.f;
; #pragma unroll
;         for (int d0 = 0; d0 < 4; ++d0) { const u32x4 qw = __builtin_bit_cast(u32x4, qr[d0]); const unsigned qq[4] = {qw.x, qw.y, qw.z, qw.w};
; #pragma unroll
;             for (int e = 0; e < 4; ++e) { const float lo = __uint_as_float(qq[e] << 16), hi_ = __uint_as_float(qq[e] & 0xffff0000u); qsq += lo * lo + hi_ * hi_; } }
;         qsq += __shfl_xor(qsq, 32);
; #pragma unroll
;         for (int o = 1; o < 32; o <<= 1) qsq = fmaxf(qsq, __shfl_xor(qsq, o));
;         LAS float* red = (LAS float*)(lds + AT_END);
;         if (lane == 0) { red[wave] = dsc; red[8 + wave] = qsq; }
	v_lshlrev_b32_e32 v36, 16, v2
	v_and_b32_e32 v2, 0xffff0000, v2
	v_mul_f32_e32 v2, v38, v2
	v_fmac_f32_e32 v2, v37, v36
	v_add_f32_e32 v2, v2, v35
	v_lshlrev_b32_e32 v35, 16, v3
	v_and_b32_e32 v3, 0xffff0000, v3
	v_lshlrev_b32_e32 v36, 16, v79
	v_mul_f32_e32 v3, v39, v3
	v_fmac_f32_e32 v3, v36, v35
	v_add_f32_e32 v2, v3, v2
	v_lshlrev_b32_e32 v3, 16, v4
	v_and_b32_e32 v4, 0xffff0000, v4
	v_lshlrev_b32_e32 v35, 16, v80
	v_mul_f32_e32 v4, v40, v4
	v_fmac_f32_e32 v4, v35, v3
	v_lshlrev_b32_e32 v3, 16, v5
	v_and_b32_e32 v5, 0xffff0000, v5
	v_add_f32_e32 v2, v4, v2
	v_lshlrev_b32_e32 v4, 16, v81
	v_mul_f32_e32 v5, v41, v5
	v_fmac_f32_e32 v5, v4, v3
	v_add_f32_e32 v2, v5, v2
	v_and_b32_e32 v5, 64, v138
	v_xor_b32_e32 v3, 32, v138
	v_add_u32_e32 v5, 64, v5
	v_cmp_lt_i32_e32 vcc, v3, v5
	v_fmac_f32_e32 v12, v36, v36
	v_add_f32_e32 v11, v12, v11
	v_cndmask_b32_e32 v3, v138, v3, vcc
	v_lshlrev_b32_e32 v42, 2, v3
	v_mov_b32_e32 v3, v2
	v_mov_b32_e32 v253, v2
	s_nop 1
	v_permlane32_swap_b32_e32 v3, v253
	v_cndmask_b32_e64 v3, v3, v253, s[98:99]
	v_mul_f32_e32 v12, v40, v40
	v_fmac_f32_e32 v12, v35, v35
	v_add_f32_e32 v11, v12, v11
	v_mul_f32_e32 v12, v41, v41
	s_waitcnt lgkmcnt(0)
	v_add_f32_e32 v2, v2, v3
	v_xor_b32_e32 v3, 1, v138
	v_cmp_lt_i32_e32 vcc, v3, v5
	v_fmac_f32_e32 v12, v4, v4
	v_add_f32_e32 v4, v12, v11
	v_cndmask_b32_e32 v3, v138, v3, vcc
	v_lshlrev_b32_e32 v43, 2, v3
	s_nop 1
	v_mov_b32_dpp v3, v2 quad_perm:[1,0,3,2] row_mask:0xf bank_mask:0xf
	v_mov_b32_e32 v11, v4
	v_mov_b32_e32 v253, v4
	s_nop 1
	v_permlane32_swap_b32_e32 v11, v253
	v_cndmask_b32_e64 v11, v11, v253, s[98:99]
	s_waitcnt lgkmcnt(1)
	v_max_f32_e32 v3, v3, v3
	v_min_f32_e32 v2, v2, v3
	v_xor_b32_e32 v3, 2, v138
	v_cmp_lt_i32_e32 vcc, v3, v5
	s_waitcnt lgkmcnt(0)
	v_add_f32_e32 v4, v4, v11
	s_nop 1
	v_mov_b32_dpp v11, v4 quad_perm:[1,0,3,2] row_mask:0xf bank_mask:0xf
	v_cndmask_b32_e32 v3, v138, v3, vcc
	v_lshlrev_b32_e32 v44, 2, v3
	s_nop 1
	v_mov_b32_dpp v3, v2 quad_perm:[2,3,0,1] row_mask:0xf bank_mask:0xf
	s_waitcnt lgkmcnt(1)
	v_max_f32_e32 v11, v11, v11
	v_max_f32_e32 v4, v4, v11
	s_nop 1
	v_mov_b32_dpp v11, v4 quad_perm:[2,3,0,1] row_mask:0xf bank_mask:0xf
	s_waitcnt lgkmcnt(1)
	v_max_f32_e32 v3, v3, v3
	v_min_f32_e32 v2, v2, v3
	v_xor_b32_e32 v3, 4, v138
	v_cmp_lt_i32_e32 vcc, v3, v5
	s_waitcnt lgkmcnt(0)
	v_max_f32_e32 v11, v11, v11
	v_max_f32_e32 v4, v4, v11
	v_cndmask_b32_e32 v3, v138, v3, vcc
	v_lshlrev_b32_e32 v45, 2, v3
	s_nop 1
	v_mov_b32_dpp v3, v2 row_shl:4 row_mask:0xf bank_mask:0x5
	s_nop 1
	v_mov_b32_dpp v3, v2 row_shr:4 row_mask:0xf bank_mask:0xa
	s_nop 1
	v_mov_b32_dpp v11, v4 row_shl:4 row_mask:0xf bank_mask:0x5
	s_nop 1
	v_mov_b32_dpp v11, v4 row_shr:4 row_mask:0xf bank_mask:0xa
	s_waitcnt lgkmcnt(1)
	v_max_f32_e32 v3, v3, v3
	v_min_f32_e32 v2, v2, v3
	v_xor_b32_e32 v3, 8, v138
	v_cmp_lt_i32_e32 vcc, v3, v5
	s_waitcnt lgkmcnt(0)
	v_max_f32_e32 v11, v11, v11
	v_max_f32_e32 v4, v4, v11
	v_cndmask_b32_e32 v3, v138, v3, vcc
	v_lshlrev_b32_e32 v46, 2, v3
	s_nop 1
	v_mov_b32_dpp v3, v2 row_ror:8 row_mask:0xf bank_mask:0xf
	s_nop 1
	v_mov_b32_dpp v11, v4 row_ror:8 row_mask:0xf bank_mask:0xf
	s_waitcnt lgkmcnt(1)
	v_max_f32_e32 v3, v3, v3
	v_min_f32_e32 v2, v2, v3
	v_xor_b32_e32 v3, 16, v138
	v_cmp_lt_i32_e32 vcc, v3, v5
	s_waitcnt lgkmcnt(0)
	v_max_f32_e32 v11, v11, v11
	v_max_f32_e32 v4, v4, v11
	v_cndmask_b32_e32 v3, v138, v3, vcc
	v_lshlrev_b32_e32 v5, 2, v3
	v_mov_b32_e32 v3, v2
	v_mov_b32_e32 v253, v2
	s_nop 1
	v_permlane16_swap_b32_e32 v3, v253
	v_cndmask_b32_e64 v3, v3, v253, s[100:101]
	v_mov_b32_e32 v5, v4
	v_mov_b32_e32 v253, v4
	s_nop 1
	v_permlane16_swap_b32_e32 v5, v253
	v_cndmask_b32_e64 v5, v5, v253, s[100:101]
	v_cmp_eq_u32_e32 vcc, 0, v8
	s_and_saveexec_b64 s[0:1], vcc
	s_cbranch_execz .LBB0_505
	s_waitcnt lgkmcnt(1)
	v_max_f32_e32 v3, v3, v3
	v_max_f32_e32 v2, v2, v2
	v_readlane_b32 s3, v255, 2
	s_waitcnt lgkmcnt(0)
	v_max_f32_e32 v5, v5, v5
	v_max_f32_e32 v4, v4, v4
	v_min_f32_e32 v2, v2, v3
	v_mov_b32_e32 v3, s3
	v_max_f32_e32 v4, v4, v5
	v_add_u32_e32 v3, 0x9800, v3
	ds_write2_b32 v3, v2, v4 offset0:128 offset1:136
